# early poll: thread 0 issues its first poll of the barrier word right after arriving, loop-head vmcnt(0) skipped while a wait is pending
# speedup vs baseline: 1.0272x; 1.0038x over previous
; __device__ __forceinline__ unsigned xb_ld(unsigned* p)              { return __hip_atomic_load(p, __ATOMIC_RELAXED, __HIP_MEMORY_SCOPE_AGENT); }
; #define XB_SPIN(cond, bar) do { unsigned _sp = 0; while (cond) { __builtin_amdgcn_s_sleep(1); \
;     if ((++_sp & 255u) == 0u) { if (xb_ld(&(bar)[XB_TMO])) break; if (_sp > XB_SPIN_CAP) { atomicAdd(&(bar)[XB_TMO], 1u); break; } } } } while (0)
; __device__ __forceinline__ void xcd_barrier(const XcdBarrier& b) {
;     ...
;         XB_SPIN((int)(xb_ld(&bar[XB_TOP]) - target) < 0, bar);
;         asm volatile("s_waitcnt vmcnt(0)" ::: "memory");
;         b.st[2] = target;
.LBB0_8:
	s_or_b64 exec, exec, s[16:17]
	v_readlane_b32 s4, v253, 29
	v_readfirstlane_b32 s101, v0
	s_nop 1
	v_mov_b32_e32 v1, s4
	ds_write_b32 v1, v0
	v_mov_b32_e32 v250, 0x3400
	v_mov_b32_e32 v251, 0
	s_nop 0
	v_lshl_add_u64 v[248:249], s[92:93], 0, v[250:251]
	global_load_dword v250, v[248:249], off sc1

; __global__ void __launch_bounds__(NTHR, 2) dit_fwd(Args args) {
;     ...
;     for (int st = args.ph_lo; st < args.ph_hi; ++st) {
;         int tid = tid_of(wave0); asm volatile("" : "+v"(tid));
;         int G = gridDim.x, bx = blockIdx.x; asm volatile("" : "+s"(G), "+s"(bx));
;         size_t wso = 0; asm volatile("" : "+s"(wso));
;         unsigned char* ws = args.ws + wso;
;         const int lane = tid & 63, wave = __builtin_amdgcn_readfirstlane(tid >> 6);
;         bf16_t* HX = (bf16_t*)(ws + WS_HX); bf16_t* Yb = (bf16_t*)(ws + WS_Y); bf16_t* MIXb = (bf16_t*)(ws + WS_MIX); bf16_t* BIG = (bf16_t*)(ws + WS_BIG);
;         int kind = ST_NOP, l = 0, sub = -1, rw = 0, coff = 0; bool seam = false;
;         if (st == 0) { kind = ST_PRO; seam = true; }
;         else if (st == 1) { kind = ST_ROW; rw = 0; seam = true; }
.LBB0_11:
	s_mov_b32 s0, -1
	s_mov_b64 s[2:3], 0
	s_cmp_lg_u32 s100, 0
	s_cbranch_scc1 .Lp8_nowait
	s_waitcnt vmcnt(0)
.Lp8_nowait:
	v_mbcnt_lo_u32_b32 v0, s0, 0
	v_mbcnt_hi_u32_b32 v0, s0, v0
	v_readlane_b32 s0, v252, 1
	s_cmp_lt_i32 s88, 1
	s_nop 0
	v_add_u32_e32 v204, s0, v0
	v_readlane_b32 s0, v252, 2
	v_readlane_b32 s1, v252, 3
	s_load_dword s0, s[0:1], 0x0
	v_readlane_b32 s1, v252, 0
	s_mov_b32 s26, s1
	v_readfirstlane_b32 s4, v204
	s_waitcnt lgkmcnt(0)
	s_mov_b32 s11, s0
	v_writelane_b32 v253, s0, 61
	s_cbranch_scc1 .LBB0_16
	s_cmp_eq_u32 s88, 1
	s_mov_b64 s[0:1], -1
	s_cbranch_scc0 .LBB0_14
	s_mov_b64 s[0:1], 0

; __device__ __forceinline__ unsigned xb_ld(unsigned* p)              { return __hip_atomic_load(p, __ATOMIC_RELAXED, __HIP_MEMORY_SCOPE_AGENT); }
; #define XB_SPIN(cond, bar) do { unsigned _sp = 0; while (cond) { __builtin_amdgcn_s_sleep(1); \
;     if ((++_sp & 255u) == 0u) { if (xb_ld(&(bar)[XB_TMO])) break; if (_sp > XB_SPIN_CAP) { atomicAdd(&(bar)[XB_TMO], 1u); break; } } } } while (0)
; __device__ __forceinline__ void xcd_barrier(const XcdBarrier& b) {
;     ...
;         XB_SPIN((int)(xb_ld(&bar[XB_TOP]) - target) < 0, bar);
.LBB0_104:
	s_cmp_eq_u32 s100, 0
	s_cbranch_scc1 .Lp1_skip
	v_readlane_b32 s0, v254, 14
	s_nop 3
	s_cmp_eq_u32 s0, 3
	s_cbranch_scc1 .Lp1_skip
	s_mov_b32 s100, 0
	s_cmp_lg_u32 s95, 0
	s_cbranch_scc1 .Lp1_all
	s_mov_b64 s[0:1], exec
	s_mov_b64 exec, 1
	s_waitcnt vmcnt(0)
	v_readfirstlane_b32 vcc_lo, v250
	s_sub_i32 vcc_lo, vcc_lo, s101
	s_cmp_lt_i32 vcc_lo, 0
	s_cbranch_scc0 .Lp1_done
	v_mov_b32_e32 v250, 0x3400
	v_mov_b32_e32 v251, 0
	s_mov_b32 vcc_hi, 0
	v_lshl_add_u64 v[248:249], s[92:93], 0, v[250:251]

; __device__ __forceinline__ unsigned xb_ld(unsigned* p)              { return __hip_atomic_load(p, __ATOMIC_RELAXED, __HIP_MEMORY_SCOPE_AGENT); }
; #define XB_SPIN(cond, bar) do { unsigned _sp = 0; while (cond) { __builtin_amdgcn_s_sleep(1); \
;     if ((++_sp & 255u) == 0u) { if (xb_ld(&(bar)[XB_TMO])) break; if (_sp > XB_SPIN_CAP) { atomicAdd(&(bar)[XB_TMO], 1u); break; } } } } while (0)
; __device__ __forceinline__ void xcd_barrier(const XcdBarrier& b) {
;     ...
;         XB_SPIN((int)(xb_ld(&bar[XB_TOP]) - target) < 0, bar);
.LBB0_261:
	s_cmp_eq_u32 s100, 0
	s_cbranch_scc1 .Lp2_skip
	s_mov_b32 s100, 0
	v_readlane_b32 vcc_lo, v253, 35
	s_nop 3
	s_cmp_lg_u32 vcc_lo, 0
	s_cbranch_scc1 .Lp2_all
	s_mov_b64 exec, 1
	s_waitcnt vmcnt(0)
	v_readfirstlane_b32 vcc_lo, v250
	s_sub_i32 vcc_lo, vcc_lo, s101
	s_cmp_lt_i32 vcc_lo, 0
	s_cbranch_scc0 .Lp2_done
	v_readlane_b32 vcc_lo, v253, 33
	v_readlane_b32 vcc_hi, v253, 34
	v_mov_b32_e32 v250, 0x3400
	v_mov_b32_e32 v251, 0
	s_nop 1
	v_lshl_add_u64 v[248:249], vcc, 0, v[250:251]
	s_mov_b32 vcc_hi, 0
